# DIFF attention epilogue: xor 1/2/4/8 hops of the 16 subln row reductions as DPP adds, only the xor-16 hop via ds_bpermute (16 instead of 80 LDS round trips per unit)
# speedup vs baseline: 1.0140x; 1.0004x over previous
; __device__ __forceinline__ unsigned f2bf(float f) { unsigned u = __builtin_bit_cast(unsigned, f); return (u + 0x7fffu + ((u >> 16) & 1u)) >> 16; }
; __device__ __forceinline__ int crow(int r, int hi) { return (r & 3) + 8 * (r >> 2) + 4 * hi; }
; #define GATE_LOAD(NIT, RB) do { _Pragma("unroll") for (int i_ = 0; i_ < (NIT); ++i_) { const int idx_ = i_ * 64 + lane, row_ = (RB) + (idx_ >> 4), ch_ = idx_ & 15; \
;       gv[i_] = *(const u32x4*)(P.Gw + (long)row_ * 2048 + ch_ * 8); } } while (0)
; template <int DQK, int KW, bool DIFF, int SDEPTH, int QSP, int NBUF>
; __device__ __forceinline__ void attn_unit(const UnitP& P, char* lds) {
;     ...
;     bf16_t* stgp = (bf16_t*)(lds + (OUT_ALIAS ? 65536 : NBUF * (SHM_V + SHM_K) + 2048)) + (wid & 3) * 4096;
;     GATE_LOAD(4, (wid >> 2) * 16);
;     if (wid < 4) {
;       float sg[4];
; #pragma unroll
;       for (int d0 = 0; d0 < 4; ++d0) sg[d0] = P.subg[d0 * 32 + r32] * P.osc;
; #pragma unroll
;       for (int r = 0; r < 16; ++r) { float ss = 0.f;
; #pragma unroll
;         for (int d0 = 0; d0 < 4; ++d0) { const float v = o[d0][r] - P.lam * st[(d0 * 16 + r) * 64]; o[d0][r] = v; ss += v * v; }
;         ss += __shfl_xor(ss, 1); ss += __shfl_xor(ss, 2); ss += __shfl_xor(ss, 4); ss += __shfl_xor(ss, 8); ss += __shfl_xor(ss, 16);
;         const float rstd = __builtin_amdgcn_rsqf(ss * (1.f / 128.f) + NORM_EPS); const int ro = crow(r, hi) * 128 + r32;
; #pragma unroll
;         for (int d0 = 0; d0 < 4; ++d0) stgp[ro + d0 * 32] = (bf16_t)f2bf(o[d0][r] * rstd * sg[d0]); }
.LBB0_342:
	s_or_b64 exec, exec, s[8:9]
	s_lshl_b64 s[38:39], s[6:7], 1
	s_add_u32 s7, s22, s38
	s_addc_u32 s9, s23, s39
	s_lshl_b32 s6, s2, 1
	v_lshrrev_b32_e32 v4, 4, v177
	s_add_u32 s8, s7, s6
	v_lshl_or_b32 v32, v165, 4, v4
	s_addc_u32 s9, s9, 0
	v_ashrrev_i32_e32 v33, 31, v32
	v_or_b32_e32 v28, 4, v32
	v_or_b32_e32 v26, 8, v32
	v_or_b32_e32 v20, 12, v32
	v_lshl_add_u64 v[2:3], s[8:9], 0, v[0:1]
	v_lshlrev_b64 v[30:31], 12, v[32:33]
	v_ashrrev_i32_e32 v29, 31, v28
	v_ashrrev_i32_e32 v27, 31, v26
	v_ashrrev_i32_e32 v21, 31, v20
	v_lshl_add_u64 v[4:5], v[2:3], 0, v[30:31]
	v_lshlrev_b64 v[24:25], 12, v[28:29]
	v_lshlrev_b64 v[22:23], 12, v[26:27]
	v_lshlrev_b64 v[18:19], 12, v[20:21]
	s_waitcnt lgkmcnt(0)
	s_barrier
	v_lshl_add_u64 v[6:7], v[2:3], 0, v[24:25]
	global_load_dwordx4 v[14:17], v[4:5], off
	global_load_dwordx4 v[10:13], v[6:7], off
	v_lshl_add_u64 v[4:5], v[2:3], 0, v[22:23]
	v_lshl_add_u64 v[2:3], v[2:3], 0, v[18:19]
	global_load_dwordx4 v[6:9], v[4:5], off
	s_nop 0
	global_load_dwordx4 v[2:5], v[2:3], off
	s_add_i32 s2, 0, 0x10000
	v_lshl_add_u32 v21, v44, 1, s2
	v_cmp_gt_i32_e32 vcc, 4, v99
	s_and_saveexec_b64 s[42:43], vcc
	s_cbranch_execz .LBB0_310
	v_lshlrev_b32_e32 v44, 2, v162
	global_load_dword v27, v44, s[4:5]
	global_load_dword v29, v44, s[4:5] offset:128
	global_load_dword v33, v44, s[4:5] offset:256
	ds_read2st64_b32 v[102:103], v47 offset1:1
	ds_read2st64_b32 v[104:105], v47 offset0:16 offset1:17
	ds_read2st64_b32 v[106:107], v47 offset0:48 offset1:49
	global_load_dword v44, v44, s[4:5] offset:384
	v_lshlrev_b32_e32 v45, 10, v175
	v_lshlrev_b32_e32 v99, 1, v162
	v_add3_u32 v45, v21, v45, v99
	s_waitcnt lgkmcnt(2)
	v_fma_f32 v97, -v172, v102, v97
	s_waitcnt lgkmcnt(1)
	v_fma_f32 v102, -v172, v104, v98
	ds_read2st64_b32 v[98:99], v47 offset0:32 offset1:33
	v_mul_f32_e32 v104, v102, v102
	v_fmac_f32_e32 v104, v97, v97
	v_fma_f32 v95, -v172, v105, v95
	v_fma_f32 v94, -v172, v103, v94
	s_waitcnt lgkmcnt(0)
	v_fma_f32 v98, -v172, v98, v100
	v_fmac_f32_e32 v104, v98, v98
	v_fma_f32 v100, -v172, v106, v101
	v_fmac_f32_e32 v104, v100, v100
	s_nop 1
	v_add_f32_dpp v104, v104, v104 quad_perm:[1,0,3,2] row_mask:0xf bank_mask:0xf
	s_nop 1
	v_add_f32_dpp v104, v104, v104 quad_perm:[2,3,0,1] row_mask:0xf bank_mask:0xf
	s_nop 1
	v_add_f32_dpp v104, v104, v104 row_half_mirror row_mask:0xf bank_mask:0xf
	s_nop 1
	v_add_f32_dpp v104, v104, v104 row_mirror row_mask:0xf bank_mask:0xf
	v_fma_f32 v96, -v172, v99, v96
	v_fma_f32 v41, -v172, v107, v41
	s_waitcnt lgkmcnt(0)
	v_mov_b32_e32 v101, v104
	s_waitcnt lgkmcnt(0)
	s_waitcnt lgkmcnt(0)
	s_waitcnt lgkmcnt(0)
	ds_bpermute_b32 v104, v171, v101
	s_waitcnt lgkmcnt(0)
	v_add_f32_e32 v101, v101, v104
	v_fmamk_f32 v101, v101, 0x3c000000, v186
	v_rsq_f32_e32 v101, v101
	s_waitcnt vmcnt(3)
	v_mul_f32_e32 v27, v173, v27
	v_mul_f32_e32 v97, v97, v101
	v_mul_f32_e32 v97, v27, v97
	v_bfe_u32 v104, v97, 16, 1
	v_add3_u32 v97, v97, v104, s85
	s_waitcnt vmcnt(2)
	v_mul_f32_e32 v29, v173, v29
	ds_write_b16_d16_hi v45, v97
	v_mul_f32_e32 v97, v102, v101
	v_mul_f32_e32 v97, v29, v97
	v_bfe_u32 v102, v97, 16, 1
	v_add3_u32 v97, v97, v102, s85
	s_waitcnt vmcnt(1)
	v_mul_f32_e32 v33, v173, v33
	ds_write_b16_d16_hi v45, v97 offset:64
	v_mul_f32_e32 v97, v98, v101
	v_mul_f32_e32 v97, v33, v97
	v_bfe_u32 v98, v97, 16, 1
	v_add3_u32 v97, v97, v98, s85
	s_waitcnt vmcnt(0)
	v_mul_f32_e32 v44, v173, v44
	ds_write_b16_d16_hi v45, v97 offset:128
	v_mul_f32_e32 v97, v100, v101
	v_mul_f32_e32 v97, v44, v97
	v_bfe_u32 v98, v97, 16, 1
	v_add3_u32 v97, v97, v98, s85
	ds_write_b16_d16_hi v45, v97 offset:192
	v_mul_f32_e32 v97, v95, v95
	v_fmac_f32_e32 v97, v94, v94
	v_fmac_f32_e32 v97, v96, v96
	v_fmac_f32_e32 v97, v41, v41
	s_nop 1
	v_add_f32_dpp v97, v97, v97 quad_perm:[1,0,3,2] row_mask:0xf bank_mask:0xf
	s_nop 1
	v_add_f32_dpp v97, v97, v97 quad_perm:[2,3,0,1] row_mask:0xf bank_mask:0xf
	s_nop 1
	v_add_f32_dpp v97, v97, v97 row_half_mirror row_mask:0xf bank_mask:0xf
	s_nop 1
	v_add_f32_dpp v97, v97, v97 row_mirror row_mask:0xf bank_mask:0xf
	s_waitcnt lgkmcnt(0)
	s_nop 0
	s_waitcnt lgkmcnt(0)
	s_waitcnt lgkmcnt(0)
	s_waitcnt lgkmcnt(0)
	ds_bpermute_b32 v98, v171, v97
	s_waitcnt lgkmcnt(0)
	v_add_f32_e32 v97, v97, v98
	v_fmamk_f32 v97, v97, 0x3c000000, v186
	v_rsq_f32_e32 v97, v97
	s_nop 0
	v_mul_f32_e32 v94, v94, v97
	v_mul_f32_e32 v94, v27, v94
	v_bfe_u32 v98, v94, 16, 1
	v_add3_u32 v94, v94, v98, s85
	ds_write_b16_d16_hi v45, v94 offset:256
	v_mul_f32_e32 v94, v95, v97
	v_mul_f32_e32 v94, v29, v94
	v_bfe_u32 v95, v94, 16, 1
	v_add3_u32 v94, v94, v95, s85
	ds_write_b16_d16_hi v45, v94 offset:320
	v_mul_f32_e32 v94, v96, v97
	v_mul_f32_e32 v94, v33, v94
	v_bfe_u32 v95, v94, 16, 1
	v_mul_f32_e32 v41, v41, v97
	v_add3_u32 v94, v94, v95, s85
	v_mul_f32_e32 v41, v44, v41
	ds_write_b16_d16_hi v45, v94 offset:384
	v_bfe_u32 v94, v41, 16, 1
	v_add3_u32 v41, v41, v94, s85
	ds_read2st64_b32 v[94:95], v47 offset0:2 offset1:3
	ds_read2st64_b32 v[96:97], v47 offset0:18 offset1:19
	ds_read2st64_b32 v[98:99], v47 offset0:34 offset1:35
	ds_write_b16_d16_hi v45, v41 offset:448
	s_waitcnt lgkmcnt(3)
	v_fma_f32 v41, -v172, v94, v91
	s_waitcnt lgkmcnt(2)
	v_fma_f32 v91, -v172, v96, v92
	s_waitcnt lgkmcnt(1)
	v_fma_f32 v96, -v172, v98, v93
	ds_read2st64_b32 v[92:93], v47 offset0:50 offset1:51
	v_mul_f32_e32 v94, v91, v91
	v_fmac_f32_e32 v94, v41, v41
	v_fmac_f32_e32 v94, v96, v96
	s_waitcnt lgkmcnt(0)
	v_fma_f32 v39, -v172, v92, v39
	v_fmac_f32_e32 v94, v39, v39
	s_nop 1
	v_add_f32_dpp v94, v94, v94 quad_perm:[1,0,3,2] row_mask:0xf bank_mask:0xf
	s_nop 1
	v_add_f32_dpp v94, v94, v94 quad_perm:[2,3,0,1] row_mask:0xf bank_mask:0xf
	s_nop 1
	v_add_f32_dpp v94, v94, v94 row_half_mirror row_mask:0xf bank_mask:0xf
	s_nop 1
	v_add_f32_dpp v94, v94, v94 row_mirror row_mask:0xf bank_mask:0xf
	v_fma_f32 v38, -v172, v93, v38
	s_waitcnt lgkmcnt(0)
; __device__ __forceinline__ unsigned f2bf(float f) { unsigned u = __builtin_bit_cast(unsigned, f); return (u + 0x7fffu + ((u >> 16) & 1u)) >> 16; }
; __device__ __forceinline__ int crow(int r, int hi) { return (r & 3) + 8 * (r >> 2) + 4 * hi; }
; template <int DQK, int KW, bool DIFF, int SDEPTH, int QSP, int NBUF>
; __device__ __forceinline__ void attn_unit(const UnitP& P, char* lds) {
;     ...
;       for (int r = 0; r < 16; ++r) { float ss = 0.f;
; #pragma unroll
;         for (int d0 = 0; d0 < 4; ++d0) { const float v = o[d0][r] - P.lam * st[(d0 * 16 + r) * 64]; o[d0][r] = v; ss += v * v; }
;         ss += __shfl_xor(ss, 1); ss += __shfl_xor(ss, 2); ss += __shfl_xor(ss, 4); ss += __shfl_xor(ss, 8); ss += __shfl_xor(ss, 16);
;         const float rstd = __builtin_amdgcn_rsqf(ss * (1.f / 128.f) + NORM_EPS); const int ro = crow(r, hi) * 128 + r32;
; #pragma unroll
;         for (int d0 = 0; d0 < 4; ++d0) stgp[ro + d0 * 32] = (bf16_t)f2bf(o[d0][r] * rstd * sg[d0]); }
	v_mov_b32_e32 v92, v94
	s_waitcnt lgkmcnt(0)
	s_waitcnt lgkmcnt(0)
	s_waitcnt lgkmcnt(0)
	ds_bpermute_b32 v94, v171, v92
	s_waitcnt lgkmcnt(0)
	v_add_f32_e32 v92, v92, v94
	v_fmamk_f32 v92, v92, 0x3c000000, v186
	v_rsq_f32_e32 v92, v92
	s_nop 0
	v_mul_f32_e32 v41, v41, v92
	v_mul_f32_e32 v41, v27, v41
	v_bfe_u32 v94, v41, 16, 1
	v_add3_u32 v41, v41, v94, s85
	ds_write_b16_d16_hi v45, v41 offset:512
	v_mul_f32_e32 v41, v91, v92
	v_mul_f32_e32 v41, v29, v41
	v_bfe_u32 v91, v41, 16, 1
	v_add3_u32 v41, v41, v91, s85
	ds_write_b16_d16_hi v45, v41 offset:576
	v_mul_f32_e32 v41, v96, v92
	v_mul_f32_e32 v41, v33, v41
	v_bfe_u32 v91, v41, 16, 1
	v_mul_f32_e32 v39, v39, v92
	v_add3_u32 v41, v41, v91, s85
	v_mul_f32_e32 v39, v44, v39
	ds_write_b16_d16_hi v45, v41 offset:640
	v_bfe_u32 v41, v39, 16, 1
	v_add3_u32 v39, v39, v41, s85
	v_fma_f32 v41, -v172, v97, v89
	ds_write_b16_d16_hi v45, v39 offset:704
	v_fma_f32 v39, -v172, v95, v88
	v_mul_f32_e32 v88, v41, v41
	v_fmac_f32_e32 v88, v39, v39
	v_fma_f32 v89, -v172, v99, v90
	v_fmac_f32_e32 v88, v89, v89
	v_fmac_f32_e32 v88, v38, v38
	s_nop 1
	v_add_f32_dpp v88, v88, v88 quad_perm:[1,0,3,2] row_mask:0xf bank_mask:0xf
	s_nop 1
	v_add_f32_dpp v88, v88, v88 quad_perm:[2,3,0,1] row_mask:0xf bank_mask:0xf
	s_nop 1
	v_add_f32_dpp v88, v88, v88 row_half_mirror row_mask:0xf bank_mask:0xf
	s_nop 1
	v_add_f32_dpp v88, v88, v88 row_mirror row_mask:0xf bank_mask:0xf
	s_waitcnt lgkmcnt(0)
	s_nop 0
	s_waitcnt lgkmcnt(0)
	s_waitcnt lgkmcnt(0)
	s_waitcnt lgkmcnt(0)
	ds_bpermute_b32 v90, v171, v88
	s_waitcnt lgkmcnt(0)
	v_add_f32_e32 v88, v88, v90
	v_fmamk_f32 v88, v88, 0x3c000000, v186
	v_rsq_f32_e32 v88, v88
	s_nop 0
	v_mul_f32_e32 v39, v39, v88
	v_mul_f32_e32 v39, v27, v39
	v_bfe_u32 v90, v39, 16, 1
	v_add3_u32 v39, v39, v90, s85
	ds_write_b16_d16_hi v45, v39 offset:768
	v_mul_f32_e32 v39, v41, v88
	v_mul_f32_e32 v39, v29, v39
	v_bfe_u32 v41, v39, 16, 1
	v_add3_u32 v39, v39, v41, s85
	ds_write_b16_d16_hi v45, v39 offset:832
	v_mul_f32_e32 v39, v89, v88
	v_mul_f32_e32 v39, v33, v39
	v_bfe_u32 v41, v39, 16, 1
	v_mul_f32_e32 v38, v38, v88
	v_add3_u32 v39, v39, v41, s85
	v_mul_f32_e32 v38, v44, v38
	ds_write_b16_d16_hi v45, v39 offset:896
	v_bfe_u32 v39, v38, 16, 1
	v_add3_u32 v38, v38, v39, s85
	ds_write_b16_d16_hi v45, v38 offset:960
	ds_read2st64_b32 v[38:39], v47 offset0:4 offset1:5
	ds_read2st64_b32 v[88:89], v47 offset0:20 offset1:21
	ds_read2st64_b32 v[90:91], v47 offset0:52 offset1:53
	s_waitcnt lgkmcnt(2)
	v_fma_f32 v38, -v172, v38, v86
	s_waitcnt lgkmcnt(1)
	v_fma_f32 v41, -v172, v88, v87
	ds_read2st64_b32 v[86:87], v47 offset0:36 offset1:37
	v_mul_f32_e32 v88, v41, v41
	v_fmac_f32_e32 v88, v38, v38
	s_waitcnt lgkmcnt(1)
	v_fma_f32 v37, -v172, v90, v37
	v_fma_f32 v35, -v172, v91, v35
	s_waitcnt lgkmcnt(0)
	v_fma_f32 v36, -v172, v86, v36
	v_fmac_f32_e32 v88, v36, v36
	v_fmac_f32_e32 v88, v37, v37
	s_nop 1
	v_add_f32_dpp v88, v88, v88 quad_perm:[1,0,3,2] row_mask:0xf bank_mask:0xf
	s_nop 1
	v_add_f32_dpp v88, v88, v88 quad_perm:[2,3,0,1] row_mask:0xf bank_mask:0xf
	s_nop 1
	v_add_f32_dpp v88, v88, v88 row_half_mirror row_mask:0xf bank_mask:0xf
	s_nop 1
	v_add_f32_dpp v88, v88, v88 row_mirror row_mask:0xf bank_mask:0xf
	v_fma_f32 v34, -v172, v87, v34
	s_waitcnt lgkmcnt(0)
	v_mov_b32_e32 v86, v88
	s_waitcnt lgkmcnt(0)
	s_waitcnt lgkmcnt(0)
	s_waitcnt lgkmcnt(0)
	ds_bpermute_b32 v88, v171, v86
	s_waitcnt lgkmcnt(0)
	v_add_f32_e32 v86, v86, v88
	v_fmamk_f32 v86, v86, 0x3c000000, v186
	v_rsq_f32_e32 v86, v86
	s_nop 0
	v_mul_f32_e32 v38, v38, v86
	v_mul_f32_e32 v38, v27, v38
	v_bfe_u32 v88, v38, 16, 1
	v_add3_u32 v38, v38, v88, s85
	ds_write_b16_d16_hi v45, v38 offset:2048
	v_mul_f32_e32 v38, v41, v86
	v_mul_f32_e32 v38, v29, v38
	v_bfe_u32 v41, v38, 16, 1
	v_mul_f32_e32 v36, v36, v86
	v_add3_u32 v38, v38, v41, s85
	v_mul_f32_e32 v36, v33, v36
	ds_write_b16_d16_hi v45, v38 offset:2112
	v_bfe_u32 v38, v36, 16, 1
	v_add3_u32 v36, v36, v38, s85
	ds_write_b16_d16_hi v45, v36 offset:2176
	v_mul_f32_e32 v36, v37, v86
	v_mul_f32_e32 v36, v44, v36
	v_bfe_u32 v37, v36, 16, 1
	v_add3_u32 v36, v36, v37, s85
	v_fma_f32 v37, -v172, v89, v85
	ds_write_b16_d16_hi v45, v36 offset:2240
	v_fma_f32 v36, -v172, v39, v84
	v_mul_f32_e32 v38, v37, v37
	v_fmac_f32_e32 v38, v36, v36
	v_fmac_f32_e32 v38, v34, v34
	v_fmac_f32_e32 v38, v35, v35
	s_nop 1
	v_add_f32_dpp v38, v38, v38 quad_perm:[1,0,3,2] row_mask:0xf bank_mask:0xf
	s_nop 1
	v_add_f32_dpp v38, v38, v38 quad_perm:[2,3,0,1] row_mask:0xf bank_mask:0xf
	s_nop 1
	v_add_f32_dpp v38, v38, v38 row_half_mirror row_mask:0xf bank_mask:0xf
	s_nop 1
	v_add_f32_dpp v38, v38, v38 row_mirror row_mask:0xf bank_mask:0xf
	s_waitcnt lgkmcnt(0)
	s_nop 0
	s_waitcnt lgkmcnt(0)
	s_waitcnt lgkmcnt(0)
	s_waitcnt lgkmcnt(0)
	ds_bpermute_b32 v39, v171, v38
	s_waitcnt lgkmcnt(0)
	v_add_f32_e32 v38, v38, v39
	v_fmamk_f32 v38, v38, 0x3c000000, v186
	v_rsq_f32_e32 v38, v38
	s_nop 0
	v_mul_f32_e32 v36, v36, v38
	v_mul_f32_e32 v36, v27, v36
	v_bfe_u32 v39, v36, 16, 1
	v_add3_u32 v36, v36, v39, s85
	ds_write_b16_d16_hi v45, v36 offset:2304
	v_mul_f32_e32 v36, v37, v38
	v_mul_f32_e32 v36, v29, v36
	v_bfe_u32 v37, v36, 16, 1
	v_mul_f32_e32 v34, v34, v38
	v_add3_u32 v36, v36, v37, s85
	v_mul_f32_e32 v34, v33, v34
	ds_write_b16_d16_hi v45, v36 offset:2368
	v_bfe_u32 v36, v34, 16, 1
	v_add3_u32 v34, v34, v36, s85
	ds_write_b16_d16_hi v45, v34 offset:2432
	v_mul_f32_e32 v34, v35, v38
	v_mul_f32_e32 v34, v44, v34
	v_bfe_u32 v35, v34, 16, 1
	v_add3_u32 v34, v34, v35, s85
	ds_write_b16_d16_hi v45, v34 offset:2496
	ds_read2st64_b32 v[34:35], v47 offset0:6 offset1:7
	ds_read2st64_b32 v[36:37], v47 offset0:22 offset1:23
	ds_read2st64_b32 v[38:39], v47 offset0:38 offset1:39
	s_waitcnt lgkmcnt(2)
; __device__ __forceinline__ unsigned f2bf(float f) { unsigned u = __builtin_bit_cast(unsigned, f); return (u + 0x7fffu + ((u >> 16) & 1u)) >> 16; }
; __device__ __forceinline__ int crow(int r, int hi) { return (r & 3) + 8 * (r >> 2) + 4 * hi; }
; template <int DQK, int KW, bool DIFF, int SDEPTH, int QSP, int NBUF>
; __device__ __forceinline__ void attn_unit(const UnitP& P, char* lds) {
;     ...
;       for (int r = 0; r < 16; ++r) { float ss = 0.f;
; #pragma unroll
;         for (int d0 = 0; d0 < 4; ++d0) { const float v = o[d0][r] - P.lam * st[(d0 * 16 + r) * 64]; o[d0][r] = v; ss += v * v; }
;         ss += __shfl_xor(ss, 1); ss += __shfl_xor(ss, 2); ss += __shfl_xor(ss, 4); ss += __shfl_xor(ss, 8); ss += __shfl_xor(ss, 16);
;         const float rstd = __builtin_amdgcn_rsqf(ss * (1.f / 128.f) + NORM_EPS); const int ro = crow(r, hi) * 128 + r32;
; #pragma unroll
;         for (int d0 = 0; d0 < 4; ++d0) stgp[ro + d0 * 32] = (bf16_t)f2bf(o[d0][r] * rstd * sg[d0]); }
	v_fma_f32 v34, -v172, v34, v82
	s_waitcnt lgkmcnt(1)
	v_fma_f32 v36, -v172, v36, v83
	s_waitcnt lgkmcnt(0)
	v_fma_f32 v38, -v172, v38, v40
	ds_read2st64_b32 v[40:41], v47 offset0:54 offset1:55
	v_mul_f32_e32 v82, v36, v36
	v_fmac_f32_e32 v82, v34, v34
	v_fmac_f32_e32 v82, v38, v38
	s_waitcnt lgkmcnt(0)
	v_fma_f32 v40, -v172, v40, v81
	v_fmac_f32_e32 v82, v40, v40
	s_nop 1
	v_add_f32_dpp v82, v82, v82 quad_perm:[1,0,3,2] row_mask:0xf bank_mask:0xf
	s_nop 1
	v_add_f32_dpp v82, v82, v82 quad_perm:[2,3,0,1] row_mask:0xf bank_mask:0xf
	s_nop 1
	v_add_f32_dpp v82, v82, v82 row_half_mirror row_mask:0xf bank_mask:0xf
	s_nop 1
	v_add_f32_dpp v82, v82, v82 row_mirror row_mask:0xf bank_mask:0xf
	s_waitcnt lgkmcnt(0)
	v_mov_b32_e32 v81, v82
	s_waitcnt lgkmcnt(0)
	s_waitcnt lgkmcnt(0)
	s_waitcnt lgkmcnt(0)
	ds_bpermute_b32 v82, v171, v81
	s_waitcnt lgkmcnt(0)
	v_add_f32_e32 v81, v81, v82
	v_fmamk_f32 v81, v81, 0x3c000000, v186
	v_rsq_f32_e32 v81, v81
	s_nop 0
	v_mul_f32_e32 v34, v34, v81
	v_mul_f32_e32 v34, v27, v34
	v_bfe_u32 v82, v34, 16, 1
	v_add3_u32 v34, v34, v82, s85
	ds_write_b16_d16_hi v45, v34 offset:2560
	v_mul_f32_e32 v34, v36, v81
	v_mul_f32_e32 v34, v29, v34
	v_bfe_u32 v36, v34, 16, 1
	v_add3_u32 v34, v34, v36, s85
	ds_write_b16_d16_hi v45, v34 offset:2624
	v_mul_f32_e32 v34, v38, v81
	v_mul_f32_e32 v34, v33, v34
	v_bfe_u32 v36, v34, 16, 1
	v_add3_u32 v34, v34, v36, s85
	ds_write_b16_d16_hi v45, v34 offset:2688
	v_mul_f32_e32 v34, v40, v81
	v_mul_f32_e32 v34, v44, v34
	v_bfe_u32 v36, v34, 16, 1
	v_add3_u32 v34, v34, v36, s85
	ds_write_b16_d16_hi v45, v34 offset:2752
	v_fma_f32 v34, -v172, v35, v77
	v_fma_f32 v35, -v172, v37, v78
	v_mul_f32_e32 v36, v35, v35
	v_fmac_f32_e32 v36, v34, v34
	v_fma_f32 v37, -v172, v39, v79
	v_fmac_f32_e32 v36, v37, v37
	v_fma_f32 v38, -v172, v41, v80
	v_fmac_f32_e32 v36, v38, v38
	s_nop 1
	v_add_f32_dpp v36, v36, v36 quad_perm:[1,0,3,2] row_mask:0xf bank_mask:0xf
	s_nop 1
	v_add_f32_dpp v36, v36, v36 quad_perm:[2,3,0,1] row_mask:0xf bank_mask:0xf
	s_nop 1
	v_add_f32_dpp v36, v36, v36 row_half_mirror row_mask:0xf bank_mask:0xf
	s_nop 1
	v_add_f32_dpp v36, v36, v36 row_mirror row_mask:0xf bank_mask:0xf
	ds_read2st64_b32 v[40:41], v47 offset0:56 offset1:57
	s_waitcnt lgkmcnt(0)
	s_nop 0
	s_waitcnt lgkmcnt(0)
	v_fma_f32 v40, -v172, v40, v76
	s_waitcnt lgkmcnt(0)
	s_waitcnt lgkmcnt(0)
	s_waitcnt lgkmcnt(0)
	ds_bpermute_b32 v39, v171, v36
	s_waitcnt lgkmcnt(0)
	v_add_f32_e32 v36, v36, v39
	v_fmamk_f32 v36, v36, 0x3c000000, v186
	v_rsq_f32_e32 v36, v36
	s_nop 0
	v_mul_f32_e32 v34, v34, v36
	v_mul_f32_e32 v34, v27, v34
	v_bfe_u32 v39, v34, 16, 1
	v_add3_u32 v34, v34, v39, s85
	ds_write_b16_d16_hi v45, v34 offset:2816
	v_mul_f32_e32 v34, v35, v36
	v_mul_f32_e32 v34, v29, v34
	v_bfe_u32 v35, v34, 16, 1
	v_add3_u32 v34, v34, v35, s85
	ds_write_b16_d16_hi v45, v34 offset:2880
	v_mul_f32_e32 v34, v37, v36
	v_mul_f32_e32 v34, v33, v34
	v_bfe_u32 v35, v34, 16, 1
	v_add3_u32 v34, v34, v35, s85
	ds_write_b16_d16_hi v45, v34 offset:2944
	v_mul_f32_e32 v34, v38, v36
	v_mul_f32_e32 v34, v44, v34
	v_bfe_u32 v35, v34, 16, 1
	v_add3_u32 v34, v34, v35, s85
	ds_write_b16_d16_hi v45, v34 offset:3008
	ds_read2st64_b32 v[34:35], v47 offset0:8 offset1:9
	ds_read2st64_b32 v[36:37], v47 offset0:24 offset1:25
	ds_read2st64_b32 v[38:39], v47 offset0:40 offset1:41
	s_waitcnt lgkmcnt(2)
	v_fma_f32 v34, -v172, v34, v74
	s_waitcnt lgkmcnt(1)
	v_fma_f32 v36, -v172, v36, v75
	v_mul_f32_e32 v74, v36, v36
	v_fmac_f32_e32 v74, v34, v34
	s_waitcnt lgkmcnt(0)
	v_fma_f32 v38, -v172, v38, v65
	v_fmac_f32_e32 v74, v38, v38
	v_fmac_f32_e32 v74, v40, v40
	s_nop 1
	v_add_f32_dpp v74, v74, v74 quad_perm:[1,0,3,2] row_mask:0xf bank_mask:0xf
	s_nop 1
	v_add_f32_dpp v74, v74, v74 quad_perm:[2,3,0,1] row_mask:0xf bank_mask:0xf
	s_nop 1
	v_add_f32_dpp v74, v74, v74 row_half_mirror row_mask:0xf bank_mask:0xf
	s_nop 1
	v_add_f32_dpp v74, v74, v74 row_mirror row_mask:0xf bank_mask:0xf
	s_waitcnt lgkmcnt(0)
	v_mov_b32_e32 v65, v74
	s_waitcnt lgkmcnt(0)
	s_waitcnt lgkmcnt(0)
	s_waitcnt lgkmcnt(0)
	ds_bpermute_b32 v74, v171, v65
	s_waitcnt lgkmcnt(0)
	v_add_f32_e32 v65, v65, v74
	v_fmamk_f32 v65, v65, 0x3c000000, v186
	v_rsq_f32_e32 v65, v65
	s_nop 0
	v_mul_f32_e32 v34, v34, v65
	v_mul_f32_e32 v34, v27, v34
	v_bfe_u32 v74, v34, 16, 1
	v_add3_u32 v34, v34, v74, s85
	ds_write_b16_d16_hi v45, v34 offset:4096
	v_mul_f32_e32 v34, v36, v65
	v_mul_f32_e32 v34, v29, v34
	v_bfe_u32 v36, v34, 16, 1
	v_add3_u32 v34, v34, v36, s85
	ds_write_b16_d16_hi v45, v34 offset:4160
	v_mul_f32_e32 v34, v38, v65
	v_mul_f32_e32 v34, v33, v34
	v_bfe_u32 v36, v34, 16, 1
	v_add3_u32 v34, v34, v36, s85
	ds_write_b16_d16_hi v45, v34 offset:4224
	v_mul_f32_e32 v34, v40, v65
	v_mul_f32_e32 v34, v44, v34
	v_bfe_u32 v36, v34, 16, 1
	v_add3_u32 v34, v34, v36, s85
	ds_write_b16_d16_hi v45, v34 offset:4288
	v_fma_f32 v34, -v172, v35, v72
	v_fma_f32 v35, -v172, v37, v73
	v_mul_f32_e32 v36, v35, v35
	v_fmac_f32_e32 v36, v34, v34
	v_fma_f32 v37, -v172, v39, v63
	v_fmac_f32_e32 v36, v37, v37
	v_fma_f32 v38, -v172, v41, v64
	v_fmac_f32_e32 v36, v38, v38
	s_nop 1
	v_add_f32_dpp v36, v36, v36 quad_perm:[1,0,3,2] row_mask:0xf bank_mask:0xf
	s_nop 1
	v_add_f32_dpp v36, v36, v36 quad_perm:[2,3,0,1] row_mask:0xf bank_mask:0xf
	s_nop 1
	v_add_f32_dpp v36, v36, v36 row_half_mirror row_mask:0xf bank_mask:0xf
	s_nop 1
	v_add_f32_dpp v36, v36, v36 row_mirror row_mask:0xf bank_mask:0xf
	ds_read2st64_b32 v[40:41], v47 offset0:58 offset1:59
	s_waitcnt lgkmcnt(0)
	s_nop 0
	s_waitcnt lgkmcnt(0)
	v_fma_f32 v40, -v172, v40, v62
	s_waitcnt lgkmcnt(0)
	s_waitcnt lgkmcnt(0)
	s_waitcnt lgkmcnt(0)
	ds_bpermute_b32 v39, v171, v36
	s_waitcnt lgkmcnt(0)
; __device__ __forceinline__ unsigned f2bf(float f) { unsigned u = __builtin_bit_cast(unsigned, f); return (u + 0x7fffu + ((u >> 16) & 1u)) >> 16; }
; __device__ __forceinline__ int crow(int r, int hi) { return (r & 3) + 8 * (r >> 2) + 4 * hi; }
; template <int DQK, int KW, bool DIFF, int SDEPTH, int QSP, int NBUF>
; __device__ __forceinline__ void attn_unit(const UnitP& P, char* lds) {
;     ...
;       for (int r = 0; r < 16; ++r) { float ss = 0.f;
; #pragma unroll
;         for (int d0 = 0; d0 < 4; ++d0) { const float v = o[d0][r] - P.lam * st[(d0 * 16 + r) * 64]; o[d0][r] = v; ss += v * v; }
;         ss += __shfl_xor(ss, 1); ss += __shfl_xor(ss, 2); ss += __shfl_xor(ss, 4); ss += __shfl_xor(ss, 8); ss += __shfl_xor(ss, 16);
;         const float rstd = __builtin_amdgcn_rsqf(ss * (1.f / 128.f) + NORM_EPS); const int ro = crow(r, hi) * 128 + r32;
; #pragma unroll
;         for (int d0 = 0; d0 < 4; ++d0) stgp[ro + d0 * 32] = (bf16_t)f2bf(o[d0][r] * rstd * sg[d0]); }
	v_add_f32_e32 v36, v36, v39
	v_fmamk_f32 v36, v36, 0x3c000000, v186
	v_rsq_f32_e32 v36, v36
	s_nop 0
	v_mul_f32_e32 v34, v34, v36
	v_mul_f32_e32 v34, v27, v34
	v_bfe_u32 v39, v34, 16, 1
	v_add3_u32 v34, v34, v39, s85
	ds_write_b16_d16_hi v45, v34 offset:4352
	v_mul_f32_e32 v34, v35, v36
	v_mul_f32_e32 v34, v29, v34
	v_bfe_u32 v35, v34, 16, 1
	v_add3_u32 v34, v34, v35, s85
	ds_write_b16_d16_hi v45, v34 offset:4416
	v_mul_f32_e32 v34, v37, v36
	v_mul_f32_e32 v34, v33, v34
	v_bfe_u32 v35, v34, 16, 1
	v_add3_u32 v34, v34, v35, s85
	ds_write_b16_d16_hi v45, v34 offset:4480
	v_mul_f32_e32 v34, v38, v36
	v_mul_f32_e32 v34, v44, v34
	v_bfe_u32 v35, v34, 16, 1
	v_add3_u32 v34, v34, v35, s85
	ds_write_b16_d16_hi v45, v34 offset:4544
	ds_read2st64_b32 v[34:35], v47 offset0:10 offset1:11
	ds_read2st64_b32 v[36:37], v47 offset0:26 offset1:27
	ds_read2st64_b32 v[38:39], v47 offset0:42 offset1:43
	s_waitcnt lgkmcnt(2)
	v_fma_f32 v34, -v172, v34, v71
	s_waitcnt lgkmcnt(1)
	v_fma_f32 v36, -v172, v36, v60
	v_mul_f32_e32 v60, v36, v36
	v_fmac_f32_e32 v60, v34, v34
	s_waitcnt lgkmcnt(0)
	v_fma_f32 v38, -v172, v38, v61
	v_fmac_f32_e32 v60, v38, v38
	v_fmac_f32_e32 v60, v40, v40
	s_nop 1
	v_add_f32_dpp v60, v60, v60 quad_perm:[1,0,3,2] row_mask:0xf bank_mask:0xf
	s_nop 1
	v_add_f32_dpp v60, v60, v60 quad_perm:[2,3,0,1] row_mask:0xf bank_mask:0xf
	s_nop 1
	v_add_f32_dpp v60, v60, v60 row_half_mirror row_mask:0xf bank_mask:0xf
	s_nop 1
	v_add_f32_dpp v60, v60, v60 row_mirror row_mask:0xf bank_mask:0xf
	s_waitcnt lgkmcnt(0)
	s_nop 0
	s_waitcnt lgkmcnt(0)
	s_waitcnt lgkmcnt(0)
	s_waitcnt lgkmcnt(0)
	ds_bpermute_b32 v61, v171, v60
	s_waitcnt lgkmcnt(0)
	v_add_f32_e32 v60, v60, v61
	v_fmamk_f32 v60, v60, 0x3c000000, v186
	v_rsq_f32_e32 v60, v60
	s_nop 0
	v_mul_f32_e32 v34, v34, v60
	v_mul_f32_e32 v34, v27, v34
	v_bfe_u32 v61, v34, 16, 1
	v_add3_u32 v34, v34, v61, s85
	ds_write_b16_d16_hi v45, v34 offset:4608
	v_mul_f32_e32 v34, v36, v60
	v_mul_f32_e32 v34, v29, v34
	v_bfe_u32 v36, v34, 16, 1
	v_add3_u32 v34, v34, v36, s85
	ds_write_b16_d16_hi v45, v34 offset:4672
	v_mul_f32_e32 v34, v38, v60
	v_mul_f32_e32 v34, v33, v34
	v_bfe_u32 v36, v34, 16, 1
	v_add3_u32 v34, v34, v36, s85
	ds_write_b16_d16_hi v45, v34 offset:4736
	v_mul_f32_e32 v34, v40, v60
	v_mul_f32_e32 v34, v44, v34
	v_bfe_u32 v36, v34, 16, 1
	v_add3_u32 v34, v34, v36, s85
	ds_write_b16_d16_hi v45, v34 offset:4800
	v_fma_f32 v34, -v172, v35, v70
	v_fma_f32 v35, -v172, v37, v57
	v_mul_f32_e32 v36, v35, v35
	v_fmac_f32_e32 v36, v34, v34
	v_fma_f32 v37, -v172, v39, v58
	v_fmac_f32_e32 v36, v37, v37
	v_fma_f32 v38, -v172, v41, v59
	v_fmac_f32_e32 v36, v38, v38
	s_nop 1
	v_add_f32_dpp v36, v36, v36 quad_perm:[1,0,3,2] row_mask:0xf bank_mask:0xf
	s_nop 1
	v_add_f32_dpp v36, v36, v36 quad_perm:[2,3,0,1] row_mask:0xf bank_mask:0xf
	s_nop 1
	v_add_f32_dpp v36, v36, v36 row_half_mirror row_mask:0xf bank_mask:0xf
	s_nop 1
	v_add_f32_dpp v36, v36, v36 row_mirror row_mask:0xf bank_mask:0xf
	ds_read2st64_b32 v[40:41], v47 offset0:60 offset1:61
	s_waitcnt lgkmcnt(0)
	s_nop 0
	s_waitcnt lgkmcnt(0)
	v_fma_f32 v40, -v172, v40, v56
	s_waitcnt lgkmcnt(0)
	s_waitcnt lgkmcnt(0)
	s_waitcnt lgkmcnt(0)
	ds_bpermute_b32 v39, v171, v36
	s_waitcnt lgkmcnt(0)
	v_add_f32_e32 v36, v36, v39
	v_fmamk_f32 v36, v36, 0x3c000000, v186
	v_rsq_f32_e32 v36, v36
	s_nop 0
	v_mul_f32_e32 v34, v34, v36
	v_mul_f32_e32 v34, v27, v34
	v_bfe_u32 v39, v34, 16, 1
	v_add3_u32 v34, v34, v39, s85
	ds_write_b16_d16_hi v45, v34 offset:4864
	v_mul_f32_e32 v34, v35, v36
	v_mul_f32_e32 v34, v29, v34
	v_bfe_u32 v35, v34, 16, 1
	v_add3_u32 v34, v34, v35, s85
	ds_write_b16_d16_hi v45, v34 offset:4928
	v_mul_f32_e32 v34, v37, v36
	v_mul_f32_e32 v34, v33, v34
	v_bfe_u32 v35, v34, 16, 1
	v_add3_u32 v34, v34, v35, s85
	ds_write_b16_d16_hi v45, v34 offset:4992
	v_mul_f32_e32 v34, v38, v36
	v_mul_f32_e32 v34, v44, v34
	v_bfe_u32 v35, v34, 16, 1
	v_add3_u32 v34, v34, v35, s85
	ds_write_b16_d16_hi v45, v34 offset:5056
	ds_read2st64_b32 v[34:35], v47 offset0:12 offset1:13
	ds_read2st64_b32 v[36:37], v47 offset0:28 offset1:29
	ds_read2st64_b32 v[38:39], v47 offset0:44 offset1:45
	s_waitcnt lgkmcnt(2)
	v_fma_f32 v34, -v172, v34, v69
	s_waitcnt lgkmcnt(1)
	v_fma_f32 v36, -v172, v36, v54
	v_mul_f32_e32 v54, v36, v36
	v_fmac_f32_e32 v54, v34, v34
	s_waitcnt lgkmcnt(0)
	v_fma_f32 v38, -v172, v38, v55
	v_fmac_f32_e32 v54, v38, v38
	v_fmac_f32_e32 v54, v40, v40
	s_nop 1
	v_add_f32_dpp v54, v54, v54 quad_perm:[1,0,3,2] row_mask:0xf bank_mask:0xf
	s_nop 1
	v_add_f32_dpp v54, v54, v54 quad_perm:[2,3,0,1] row_mask:0xf bank_mask:0xf
	s_nop 1
	v_add_f32_dpp v54, v54, v54 row_half_mirror row_mask:0xf bank_mask:0xf
	s_nop 1
	v_add_f32_dpp v54, v54, v54 row_mirror row_mask:0xf bank_mask:0xf
	s_waitcnt lgkmcnt(0)
	s_nop 0
	s_waitcnt lgkmcnt(0)
	s_waitcnt lgkmcnt(0)
	s_waitcnt lgkmcnt(0)
	ds_bpermute_b32 v55, v171, v54
	s_waitcnt lgkmcnt(0)
; __device__ __forceinline__ unsigned f2bf(float f) { unsigned u = __builtin_bit_cast(unsigned, f); return (u + 0x7fffu + ((u >> 16) & 1u)) >> 16; }
; __device__ __forceinline__ int crow(int r, int hi) { return (r & 3) + 8 * (r >> 2) + 4 * hi; }
; template <int DQK, int KW, bool DIFF, int SDEPTH, int QSP, int NBUF>
; __device__ __forceinline__ void attn_unit(const UnitP& P, char* lds) {
;     ...
;       for (int r = 0; r < 16; ++r) { float ss = 0.f;
; #pragma unroll
;         for (int d0 = 0; d0 < 4; ++d0) { const float v = o[d0][r] - P.lam * st[(d0 * 16 + r) * 64]; o[d0][r] = v; ss += v * v; }
;         ss += __shfl_xor(ss, 1); ss += __shfl_xor(ss, 2); ss += __shfl_xor(ss, 4); ss += __shfl_xor(ss, 8); ss += __shfl_xor(ss, 16);
;         const float rstd = __builtin_amdgcn_rsqf(ss * (1.f / 128.f) + NORM_EPS); const int ro = crow(r, hi) * 128 + r32;
; #pragma unroll
;         for (int d0 = 0; d0 < 4; ++d0) stgp[ro + d0 * 32] = (bf16_t)f2bf(o[d0][r] * rstd * sg[d0]); }
	v_add_f32_e32 v54, v54, v55
	v_fmamk_f32 v54, v54, 0x3c000000, v186
	v_rsq_f32_e32 v54, v54
	s_nop 0
	v_mul_f32_e32 v34, v34, v54
	v_mul_f32_e32 v34, v27, v34
	v_bfe_u32 v55, v34, 16, 1
	v_add3_u32 v34, v34, v55, s85
	ds_write_b16_d16_hi v45, v34 offset:6144
	v_mul_f32_e32 v34, v36, v54
	v_mul_f32_e32 v34, v29, v34
	v_bfe_u32 v36, v34, 16, 1
	v_add3_u32 v34, v34, v36, s85
	ds_write_b16_d16_hi v45, v34 offset:6208
	v_mul_f32_e32 v34, v38, v54
	v_mul_f32_e32 v34, v33, v34
	v_bfe_u32 v36, v34, 16, 1
	v_add3_u32 v34, v34, v36, s85
	ds_write_b16_d16_hi v45, v34 offset:6272
	v_mul_f32_e32 v34, v40, v54
	v_mul_f32_e32 v34, v44, v34
	v_bfe_u32 v36, v34, 16, 1
	v_add3_u32 v34, v34, v36, s85
	ds_write_b16_d16_hi v45, v34 offset:6336
	v_fma_f32 v34, -v172, v35, v68
	v_fma_f32 v35, -v172, v37, v52
	v_mul_f32_e32 v36, v35, v35
	v_fmac_f32_e32 v36, v34, v34
	v_fma_f32 v37, -v172, v39, v53
	v_fmac_f32_e32 v36, v37, v37
	v_fma_f32 v38, -v172, v41, v49
	v_fmac_f32_e32 v36, v38, v38
	s_nop 1
	v_add_f32_dpp v36, v36, v36 quad_perm:[1,0,3,2] row_mask:0xf bank_mask:0xf
	s_nop 1
	v_add_f32_dpp v36, v36, v36 quad_perm:[2,3,0,1] row_mask:0xf bank_mask:0xf
	s_nop 1
	v_add_f32_dpp v36, v36, v36 row_half_mirror row_mask:0xf bank_mask:0xf
	s_nop 1
	v_add_f32_dpp v36, v36, v36 row_mirror row_mask:0xf bank_mask:0xf
	ds_read2st64_b32 v[40:41], v47 offset0:62 offset1:63
	s_waitcnt lgkmcnt(0)
	s_nop 0
	s_waitcnt lgkmcnt(0)
	v_fma_f32 v40, -v172, v40, v46
	s_waitcnt lgkmcnt(0)
	s_waitcnt lgkmcnt(0)
	s_waitcnt lgkmcnt(0)
	ds_bpermute_b32 v39, v171, v36
	s_waitcnt lgkmcnt(0)
	v_add_f32_e32 v36, v36, v39
	v_fmamk_f32 v36, v36, 0x3c000000, v186
	v_rsq_f32_e32 v36, v36
	s_nop 0
	v_mul_f32_e32 v34, v34, v36
	v_mul_f32_e32 v34, v27, v34
	v_bfe_u32 v39, v34, 16, 1
	v_add3_u32 v34, v34, v39, s85
	ds_write_b16_d16_hi v45, v34 offset:6400
	v_mul_f32_e32 v34, v35, v36
	v_mul_f32_e32 v34, v29, v34
	v_bfe_u32 v35, v34, 16, 1
	v_add3_u32 v34, v34, v35, s85
	ds_write_b16_d16_hi v45, v34 offset:6464
	v_mul_f32_e32 v34, v37, v36
	v_mul_f32_e32 v34, v33, v34
	v_bfe_u32 v35, v34, 16, 1
	v_add3_u32 v34, v34, v35, s85
	ds_write_b16_d16_hi v45, v34 offset:6528
	v_mul_f32_e32 v34, v38, v36
	v_mul_f32_e32 v34, v44, v34
	v_bfe_u32 v35, v34, 16, 1
	v_add3_u32 v34, v34, v35, s85
	ds_write_b16_d16_hi v45, v34 offset:6592
	ds_read2st64_b32 v[34:35], v47 offset0:14 offset1:15
	ds_read2st64_b32 v[36:37], v47 offset0:30 offset1:31
	ds_read2st64_b32 v[38:39], v47 offset0:46 offset1:47
	s_waitcnt lgkmcnt(2)
	v_fma_f32 v34, -v172, v34, v67
	s_waitcnt lgkmcnt(1)
	v_fma_f32 v36, -v172, v36, v51
	v_mul_f32_e32 v49, v36, v36
	v_fmac_f32_e32 v49, v34, v34
	s_waitcnt lgkmcnt(0)
	v_fma_f32 v38, -v172, v38, v48
	v_fmac_f32_e32 v49, v38, v38
	v_fmac_f32_e32 v49, v40, v40
	s_nop 1
	v_add_f32_dpp v49, v49, v49 quad_perm:[1,0,3,2] row_mask:0xf bank_mask:0xf
	s_nop 1
	v_add_f32_dpp v49, v49, v49 quad_perm:[2,3,0,1] row_mask:0xf bank_mask:0xf
	s_nop 1
	v_add_f32_dpp v49, v49, v49 row_half_mirror row_mask:0xf bank_mask:0xf
	s_nop 1
	v_add_f32_dpp v49, v49, v49 row_mirror row_mask:0xf bank_mask:0xf
	s_waitcnt lgkmcnt(0)
	v_mov_b32_e32 v46, v49
	s_waitcnt lgkmcnt(0)
	s_waitcnt lgkmcnt(0)
	s_waitcnt lgkmcnt(0)
	ds_bpermute_b32 v47, v171, v46
	s_waitcnt lgkmcnt(0)
	v_add_f32_e32 v46, v46, v47
	v_fmamk_f32 v46, v46, 0x3c000000, v186
	v_rsq_f32_e32 v46, v46
	s_nop 0
	v_mul_f32_e32 v34, v34, v46
	v_mul_f32_e32 v34, v27, v34
	v_bfe_u32 v47, v34, 16, 1
	v_add3_u32 v34, v34, v47, s85
	ds_write_b16_d16_hi v45, v34 offset:6656
	v_mul_f32_e32 v34, v36, v46
	v_mul_f32_e32 v34, v29, v34
	v_bfe_u32 v36, v34, 16, 1
	v_add3_u32 v34, v34, v36, s85
	ds_write_b16_d16_hi v45, v34 offset:6720
	v_mul_f32_e32 v34, v38, v46
	v_mul_f32_e32 v34, v33, v34
	v_bfe_u32 v36, v34, 16, 1
	v_add3_u32 v34, v34, v36, s85
	ds_write_b16_d16_hi v45, v34 offset:6784
	v_mul_f32_e32 v34, v40, v46
	v_mul_f32_e32 v34, v44, v34
	v_bfe_u32 v36, v34, 16, 1
	v_add3_u32 v34, v34, v36, s85
	ds_write_b16_d16_hi v45, v34 offset:6848
	v_fma_f32 v34, -v172, v35, v66
	v_fma_f32 v35, -v172, v37, v50
	v_mul_f32_e32 v36, v35, v35
	v_fmac_f32_e32 v36, v34, v34
	v_fma_f32 v37, -v172, v39, v42
	v_fmac_f32_e32 v36, v37, v37
	v_fma_f32 v38, -v172, v41, v43
	v_fmac_f32_e32 v36, v38, v38
	s_nop 1
	v_add_f32_dpp v36, v36, v36 quad_perm:[1,0,3,2] row_mask:0xf bank_mask:0xf
	s_nop 1
	v_add_f32_dpp v36, v36, v36 quad_perm:[2,3,0,1] row_mask:0xf bank_mask:0xf
	s_nop 1
	v_add_f32_dpp v36, v36, v36 row_half_mirror row_mask:0xf bank_mask:0xf
	s_nop 1
	v_add_f32_dpp v36, v36, v36 row_mirror row_mask:0xf bank_mask:0xf
	s_waitcnt lgkmcnt(0)
	s_nop 0
	s_waitcnt lgkmcnt(0)
	s_waitcnt lgkmcnt(0)
	s_waitcnt lgkmcnt(0)
	ds_bpermute_b32 v39, v171, v36
	s_waitcnt lgkmcnt(0)
	v_add_f32_e32 v36, v36, v39
	v_fmamk_f32 v36, v36, 0x3c000000, v186
	v_rsq_f32_e32 v36, v36
	s_nop 0
	v_mul_f32_e32 v34, v34, v36
	v_mul_f32_e32 v27, v27, v34
	v_bfe_u32 v34, v27, 16, 1
	v_add3_u32 v27, v27, v34, s85
	ds_write_b16_d16_hi v45, v27 offset:6912
	v_mul_f32_e32 v27, v35, v36
	v_mul_f32_e32 v27, v29, v27
	v_bfe_u32 v29, v27, 16, 1
	v_add3_u32 v27, v27, v29, s85
	ds_write_b16_d16_hi v45, v27 offset:6976
	v_mul_f32_e32 v27, v37, v36
	v_mul_f32_e32 v27, v33, v27
	v_bfe_u32 v29, v27, 16, 1
	v_add3_u32 v27, v27, v29, s85
	ds_write_b16_d16_hi v45, v27 offset:7040
	v_mul_f32_e32 v27, v38, v36
	v_mul_f32_e32 v27, v44, v27
	v_bfe_u32 v29, v27, 16, 1
	v_add3_u32 v27, v27, v29, s85
	ds_write_b16_d16_hi v45, v27 offset:7104
	s_branch .LBB0_310
